# S5 per-item staging: KT table loads issued together with the U tile loads (before their wait) instead of a one-load-per-trip loop after it
# baseline (speedup 1.0000x reference)
; #define LAS __attribute__((address_space(3)))
; DEV void s5_phase(LAS char* shm, const bf16_t* Uin, bf16_t* Yout, const char* tab, const float* dskip) {
;     ...
;         const bf16_t* wsp = WS + (size_t)g * WS_G + ((size_t)(wid * 16) * 64 + lane) * 8; asm volatile("" : "+v"(wsp));
; #pragma unroll
;         for (int sp = 0; sp < 8; ++sp) wfr[sp] = *(const bf16x8*)(wsp + (size_t)sp * 64 * 8);
;         __syncthreads();
; #pragma unroll
;         for (int i = 0; i < 8; ++i) {
;             const int idx = tid + 512 * i, tok = idx >> 1, hf = idx & 1;
;             const uint4 uv = *(const uint4*)(Ub + (size_t)tok * 16 + hf * 8);
;             *(LAS u32x4*)(shm + hf * PLANE + (tok >> 5) * 528 + (tok & 31) * 16) = (u32x4){uv.x, uv.y, uv.z, uv.w};
;         }
;         for (int idx = tid; idx < 33 * 32; idx += 512) {
;             const uint4 kv = *(const uint4*)(KT + (size_t)g * KT_G + idx * 8);
;             *(LAS u32x4*)(shm + KTL + idx * 16) = (u32x4){kv.x, kv.y, kv.z, kv.w};
;         }
.LBB0_288:
	s_lshl_b32 s0, s44, 3
	s_and_b32 s0, s0, 56
	s_bfe_u32 s1, s44, 0x30003
	s_or_b32 s47, s0, s1
	s_ashr_i32 s1, s44, 6
	s_bfe_u32 s0, s44, 0x20006
	s_and_b32 s1, s1, -4
	v_mov_b32_e32 v172, v254
	s_or_b32 s0, s0, s1
	s_ashr_i32 s1, s0, 31
	v_readfirstlane_b32 s46, v172
	s_ashr_i32 s45, s46, 6
	s_lshl_b64 s[0:1], s[0:1], 15
	s_lshl_b32 s6, s47, 18
	s_add_u32 s0, s6, s0
	s_addc_u32 s1, 0, s1
	s_lshl_b64 s[8:9], s[0:1], 1
	s_add_u32 s0, s17, s8
	s_addc_u32 s1, s18, s9
	s_lshl_b32 s6, s47, 17
	s_add_u32 s12, s23, s6
	s_addc_u32 s13, s24, 0
	s_lshl_b32 s6, s45, 4
	s_ashr_i32 s7, s6, 31
	s_lshl_b64 s[10:11], s[6:7], 10
	v_and_b32_e32 v173, 63, v172
	s_add_u32 s10, s12, s10
	s_addc_u32 s11, s13, s11
	v_lshlrev_b32_e32 v166, 4, v173
	v_lshl_add_u64 v[168:169], s[10:11], 0, v[166:167]
	v_and_b32_e32 v0, 1, v172
	v_add_co_u32_e32 v2, vcc, s27, v168
	v_ashrrev_i32_e32 v66, 1, v172
	s_nop 0
	v_addc_co_u32_e32 v3, vcc, 0, v169, vcc
	global_load_dwordx4 v[46:49], v[168:169], off
	global_load_dwordx4 v[42:45], v[168:169], off offset:1024
	global_load_dwordx4 v[38:41], v[168:169], off offset:2048
	global_load_dwordx4 v[34:37], v[168:169], off offset:3072
	global_load_dwordx4 v[30:33], v[2:3], off
	global_load_dwordx4 v[26:29], v[2:3], off offset:1024
	global_load_dwordx4 v[22:25], v[2:3], off offset:2048
	global_load_dwordx4 v[18:21], v[2:3], off offset:3072
	v_lshlrev_b32_e32 v2, 4, v0
	v_mov_b32_e32 v3, v167
	v_ashrrev_i32_e32 v67, 31, v66
	v_lshl_add_u64 v[62:63], s[0:1], 0, v[2:3]
	v_lshlrev_b64 v[2:3], 5, v[66:67]
	v_add_u32_e32 v1, 0x200, v172
	v_lshl_add_u64 v[2:3], v[62:63], 0, v[2:3]
	v_ashrrev_i32_e32 v68, 1, v1
	s_waitcnt lgkmcnt(0)
	s_barrier
	global_load_dwordx4 v[2:5], v[2:3], off
	v_ashrrev_i32_e32 v69, 31, v68
	v_lshlrev_b64 v[6:7], 5, v[68:69]
	v_add_u32_e32 v67, 0x400, v172
	v_lshl_add_u64 v[6:7], v[62:63], 0, v[6:7]
	v_ashrrev_i32_e32 v70, 1, v67
	global_load_dwordx4 v[6:9], v[6:7], off
	v_ashrrev_i32_e32 v71, 31, v70
	v_lshlrev_b64 v[10:11], 5, v[70:71]
	v_add_u32_e32 v69, 0x600, v172
	v_lshl_add_u64 v[10:11], v[62:63], 0, v[10:11]
	v_ashrrev_i32_e32 v72, 1, v69
	global_load_dwordx4 v[10:13], v[10:11], off
	v_ashrrev_i32_e32 v73, 31, v72
	v_lshlrev_b64 v[14:15], 5, v[72:73]
	v_add_u32_e32 v71, 0x800, v172
	v_lshl_add_u64 v[14:15], v[62:63], 0, v[14:15]
	v_ashrrev_i32_e32 v74, 1, v71
	global_load_dwordx4 v[14:17], v[14:15], off
	v_ashrrev_i32_e32 v75, 31, v74
	v_lshlrev_b64 v[50:51], 5, v[74:75]
	v_add_u32_e32 v73, 0xa00, v172
	v_lshl_add_u64 v[50:51], v[62:63], 0, v[50:51]
	v_ashrrev_i32_e32 v76, 1, v73
	global_load_dwordx4 v[50:53], v[50:51], off
	v_ashrrev_i32_e32 v77, 31, v76
	v_lshlrev_b64 v[54:55], 5, v[76:77]
	v_add_u32_e32 v75, 0xc00, v172
	v_lshl_add_u64 v[54:55], v[62:63], 0, v[54:55]
	v_ashrrev_i32_e32 v78, 1, v75
	global_load_dwordx4 v[54:57], v[54:55], off
	v_ashrrev_i32_e32 v79, 31, v78
	v_lshlrev_b64 v[58:59], 5, v[78:79]
	v_add_u32_e32 v77, 0xe00, v172
	v_lshl_add_u64 v[58:59], v[62:63], 0, v[58:59]
	v_ashrrev_i32_e32 v80, 1, v77
	global_load_dwordx4 v[58:61], v[58:59], off
	v_ashrrev_i32_e32 v81, 31, v80
	v_lshlrev_b64 v[64:65], 5, v[80:81]
	v_lshl_add_u64 v[62:63], v[62:63], 0, v[64:65]
	global_load_dwordx4 v[62:65], v[62:63], off
	v_ashrrev_i32_e32 v79, 6, v172
	v_lshlrev_b32_e32 v66, 4, v66
	v_mad_u32_u24 v0, v0, s28, 0
	v_mul_lo_u32 v79, v79, s29
	v_and_b32_e32 v66, 0x1f0, v66
	v_add3_u32 v66, v0, v79, v66
	v_ashrrev_i32_e32 v1, 6, v1
	v_mul_lo_u32 v1, v1, s29
	v_cmp_gt_i32_e32 vcc, s30, v172
	s_mul_i32 s56, s47, 0x4200
	s_add_u32 s54, s21, s56
	s_addc_u32 s55, s22, 0
	v_lshlrev_b32_e32 v192, 3, v172
	v_mov_b32_e32 v193, 0
	v_lshl_add_u64 v[194:195], v[192:193], 1, s[54:55]
	global_load_dwordx4 v[180:183], v[194:195], off
	s_mov_b64 s[56:57], 0x2000
	v_lshl_add_u64 v[196:197], v[194:195], 0, s[56:57]
	global_load_dwordx4 v[184:187], v[196:197], off
	v_cmp_gt_i32_e64 s[60:61], 32, v172
	v_lshl_add_u64 v[196:197], v[196:197], 0, s[56:57]
	s_and_saveexec_b64 s[56:57], s[60:61]
	global_load_dwordx4 v[188:191], v[196:197], off
	s_or_b64 exec, exec, s[56:57]
	s_waitcnt vmcnt(0)
	ds_write_b128 v66, v[2:5]
	v_lshlrev_b32_e32 v2, 4, v68
	v_and_b32_e32 v2, 0x1f0, v2
	v_add3_u32 v1, v0, v1, v2
	v_lshlrev_b32_e32 v2, 4, v70
	v_and_b32_e32 v2, 0x1f0, v2
	ds_write_b128 v1, v[6:9]
	v_ashrrev_i32_e32 v1, 6, v67
	v_mul_lo_u32 v1, v1, s29
	v_add3_u32 v1, v0, v1, v2
	v_lshlrev_b32_e32 v2, 4, v72
	v_and_b32_e32 v2, 0x1f0, v2
	ds_write_b128 v1, v[10:13]
	v_ashrrev_i32_e32 v1, 6, v69
	v_mul_lo_u32 v1, v1, s29
	v_add3_u32 v1, v0, v1, v2
	v_lshlrev_b32_e32 v2, 4, v74
	v_and_b32_e32 v2, 0x1f0, v2
	ds_write_b128 v1, v[14:17]
	v_ashrrev_i32_e32 v1, 6, v71
	v_mul_lo_u32 v1, v1, s29
	v_add3_u32 v1, v0, v1, v2
	v_lshlrev_b32_e32 v2, 4, v76
	v_and_b32_e32 v2, 0x1f0, v2
	ds_write_b128 v1, v[50:53]
	v_ashrrev_i32_e32 v1, 6, v73
	v_mul_lo_u32 v1, v1, s29
	v_add3_u32 v1, v0, v1, v2
	v_lshlrev_b32_e32 v2, 4, v78
	v_and_b32_e32 v2, 0x1f0, v2
	ds_write_b128 v1, v[54:57]
	v_ashrrev_i32_e32 v1, 6, v75
	v_mul_lo_u32 v1, v1, s29
	v_add3_u32 v1, v0, v1, v2
	v_lshlrev_b32_e32 v2, 4, v80
	v_and_b32_e32 v2, 0x1f0, v2
	ds_write_b128 v1, v[58:61]
	v_ashrrev_i32_e32 v1, 6, v77
	v_mul_lo_u32 v1, v1, s29
	v_add3_u32 v0, v0, v1, v2
	ds_write_b128 v0, v[62:65]
	s_and_saveexec_b64 s[0:1], vcc
	s_cbranch_execz .LBB0_291
	s_mul_i32 s7, s47, 0x4200
	s_add_u32 s10, s21, s7
	s_addc_u32 s11, s22, 0
	v_add_u32_e32 v4, 0xfffffe00, v172
	v_lshl_add_u32 v5, v172, 4, s31
	v_lshlrev_b32_e32 v2, 3, v172
	s_mov_b64 s[12:13], 0
.LBB0_290:
	ds_write_b128 v5, v[180:183]
	ds_write_b128 v5, v[184:187] offset:8192
	s_and_saveexec_b64 s[56:57], s[60:61]
	ds_write_b128 v5, v[188:191] offset:16384
	s_or_b64 exec, exec, s[56:57]

; #define LAS __attribute__((address_space(3)))
; DEV void s5_phase(LAS char* shm, const bf16_t* Uin, bf16_t* Yout, const char* tab, const float* dskip) {
;     ...
;         const bf16_t* wsp = WS + (size_t)g * WS_G + ((size_t)(wid * 16) * 64 + lane) * 8; asm volatile("" : "+v"(wsp));
; #pragma unroll
;         for (int sp = 0; sp < 8; ++sp) wfr[sp] = *(const bf16x8*)(wsp + (size_t)sp * 64 * 8);
;         __syncthreads();
; #pragma unroll
;         for (int i = 0; i < 8; ++i) {
;             const int idx = tid + 512 * i, tok = idx >> 1, hf = idx & 1;
;             const uint4 uv = *(const uint4*)(Ub + (size_t)tok * 16 + hf * 8);
;             *(LAS u32x4*)(shm + hf * PLANE + (tok >> 5) * 528 + (tok & 31) * 16) = (u32x4){uv.x, uv.y, uv.z, uv.w};
;         }
;         for (int idx = tid; idx < 33 * 32; idx += 512) {
;             const uint4 kv = *(const uint4*)(KT + (size_t)g * KT_G + idx * 8);
;             *(LAS u32x4*)(shm + KTL + idx * 16) = (u32x4){kv.x, kv.y, kv.z, kv.w};
;         }
.LBB0_1143:
	s_lshl_b32 s0, s42, 3
	s_and_b32 s0, s0, 56
	s_bfe_u32 s1, s42, 0x30003
	s_or_b32 s45, s0, s1
	s_ashr_i32 s1, s42, 6
	s_bfe_u32 s0, s42, 0x20006
	s_and_b32 s1, s1, -4
	v_mov_b32_e32 v172, v254
	s_or_b32 s0, s0, s1
	s_ashr_i32 s1, s0, 31
	v_readfirstlane_b32 s44, v172
	s_ashr_i32 s43, s44, 6
	s_lshl_b64 s[0:1], s[0:1], 15
	s_lshl_b32 s6, s45, 18
	s_add_u32 s0, s6, s0
	s_addc_u32 s1, 0, s1
	s_lshl_b64 s[8:9], s[0:1], 1
	s_add_u32 s0, s15, s8
	s_addc_u32 s1, s16, s9
	s_lshl_b32 s6, s45, 17
	s_add_u32 s12, s23, s6
	s_addc_u32 s13, s24, 0
	s_lshl_b32 s6, s43, 4
	s_ashr_i32 s7, s6, 31
	s_lshl_b64 s[10:11], s[6:7], 10
	v_and_b32_e32 v173, 63, v172
	s_add_u32 s10, s12, s10
	s_addc_u32 s11, s13, s11
	v_lshlrev_b32_e32 v166, 4, v173
	v_lshl_add_u64 v[168:169], s[10:11], 0, v[166:167]
	v_and_b32_e32 v82, 1, v172
	v_add_co_u32_e32 v0, vcc, s27, v168
	v_ashrrev_i32_e32 v66, 1, v172
	s_nop 0
	v_addc_co_u32_e32 v1, vcc, 0, v169, vcc
	global_load_dwordx4 v[46:49], v[168:169], off
	global_load_dwordx4 v[42:45], v[168:169], off offset:1024
	global_load_dwordx4 v[38:41], v[168:169], off offset:2048
	global_load_dwordx4 v[34:37], v[168:169], off offset:3072
	global_load_dwordx4 v[30:33], v[0:1], off
	global_load_dwordx4 v[26:29], v[0:1], off offset:1024
	global_load_dwordx4 v[22:25], v[0:1], off offset:2048
	global_load_dwordx4 v[18:21], v[0:1], off offset:3072
	v_lshlrev_b32_e32 v0, 4, v82
	v_mov_b32_e32 v1, v167
	v_ashrrev_i32_e32 v67, 31, v66
	v_lshl_add_u64 v[0:1], s[0:1], 0, v[0:1]
	v_lshlrev_b64 v[2:3], 5, v[66:67]
	v_add_u32_e32 v67, 0x200, v172
	v_lshl_add_u64 v[2:3], v[0:1], 0, v[2:3]
	v_ashrrev_i32_e32 v68, 1, v67
	s_waitcnt lgkmcnt(0)
	s_barrier
	global_load_dwordx4 v[2:5], v[2:3], off
	v_ashrrev_i32_e32 v69, 31, v68
	v_lshlrev_b64 v[6:7], 5, v[68:69]
	v_add_u32_e32 v69, 0x400, v172
	v_lshl_add_u64 v[6:7], v[0:1], 0, v[6:7]
	v_ashrrev_i32_e32 v70, 1, v69
	global_load_dwordx4 v[6:9], v[6:7], off
	v_ashrrev_i32_e32 v71, 31, v70
	v_lshlrev_b64 v[10:11], 5, v[70:71]
	v_add_u32_e32 v71, 0x600, v172
	v_lshl_add_u64 v[10:11], v[0:1], 0, v[10:11]
	v_ashrrev_i32_e32 v72, 1, v71
	global_load_dwordx4 v[10:13], v[10:11], off
	v_ashrrev_i32_e32 v73, 31, v72
	v_lshlrev_b64 v[14:15], 5, v[72:73]
	v_add_u32_e32 v73, 0x800, v172
	v_lshl_add_u64 v[14:15], v[0:1], 0, v[14:15]
	v_ashrrev_i32_e32 v74, 1, v73
	global_load_dwordx4 v[14:17], v[14:15], off
	v_ashrrev_i32_e32 v75, 31, v74
	v_lshlrev_b64 v[50:51], 5, v[74:75]
	v_add_u32_e32 v75, 0xa00, v172
	v_lshl_add_u64 v[50:51], v[0:1], 0, v[50:51]
	v_ashrrev_i32_e32 v76, 1, v75
	global_load_dwordx4 v[50:53], v[50:51], off
	v_ashrrev_i32_e32 v77, 31, v76
	v_lshlrev_b64 v[54:55], 5, v[76:77]
	v_add_u32_e32 v77, 0xc00, v172
	v_lshl_add_u64 v[54:55], v[0:1], 0, v[54:55]
	v_ashrrev_i32_e32 v78, 1, v77
	global_load_dwordx4 v[54:57], v[54:55], off
	v_ashrrev_i32_e32 v79, 31, v78
	v_lshlrev_b64 v[58:59], 5, v[78:79]
	v_add_u32_e32 v79, 0xe00, v172
	v_lshl_add_u64 v[58:59], v[0:1], 0, v[58:59]
	v_ashrrev_i32_e32 v80, 1, v79
	global_load_dwordx4 v[58:61], v[58:59], off
	v_ashrrev_i32_e32 v81, 31, v80
	v_lshlrev_b64 v[62:63], 5, v[80:81]
	v_lshl_add_u64 v[0:1], v[0:1], 0, v[62:63]
	global_load_dwordx4 v[62:65], v[0:1], off
	v_ashrrev_i32_e32 v1, 6, v172
	v_lshlrev_b32_e32 v66, 4, v66
	v_mad_u32_u24 v0, v82, s28, 0
	v_mul_lo_u32 v1, v1, s29
	v_and_b32_e32 v66, 0x1f0, v66
	v_add3_u32 v1, v0, v1, v66
	v_cmp_gt_i32_e32 vcc, s30, v172
	s_mul_i32 s56, s45, 0x4200
	s_add_u32 s54, s19, s56
	s_addc_u32 s55, s20, 0
	v_lshlrev_b32_e32 v192, 3, v172
	v_mov_b32_e32 v193, 0
	v_lshl_add_u64 v[194:195], v[192:193], 1, s[54:55]
	global_load_dwordx4 v[180:183], v[194:195], off
	s_mov_b64 s[56:57], 0x2000
	v_lshl_add_u64 v[196:197], v[194:195], 0, s[56:57]
	global_load_dwordx4 v[184:187], v[196:197], off
	v_cmp_gt_i32_e64 s[60:61], 32, v172
	v_lshl_add_u64 v[196:197], v[196:197], 0, s[56:57]
	s_and_saveexec_b64 s[56:57], s[60:61]
	global_load_dwordx4 v[188:191], v[196:197], off
	s_or_b64 exec, exec, s[56:57]
	s_waitcnt vmcnt(0)
	ds_write_b128 v1, v[2:5]
	v_ashrrev_i32_e32 v1, 6, v67
	v_lshlrev_b32_e32 v2, 4, v68
	v_mul_lo_u32 v1, v1, s29
	v_and_b32_e32 v2, 0x1f0, v2
	v_add3_u32 v1, v0, v1, v2
	ds_write_b128 v1, v[6:9]
	v_ashrrev_i32_e32 v1, 6, v69
	v_lshlrev_b32_e32 v2, 4, v70
	v_mul_lo_u32 v1, v1, s29
	v_and_b32_e32 v2, 0x1f0, v2
	v_add3_u32 v1, v0, v1, v2
	ds_write_b128 v1, v[10:13]
	v_ashrrev_i32_e32 v1, 6, v71
	v_lshlrev_b32_e32 v2, 4, v72
	v_mul_lo_u32 v1, v1, s29
	v_and_b32_e32 v2, 0x1f0, v2
	v_add3_u32 v1, v0, v1, v2
	ds_write_b128 v1, v[14:17]
	v_ashrrev_i32_e32 v1, 6, v73
	v_lshlrev_b32_e32 v2, 4, v74
	v_mul_lo_u32 v1, v1, s29
	v_and_b32_e32 v2, 0x1f0, v2
	v_add3_u32 v1, v0, v1, v2
	ds_write_b128 v1, v[50:53]
	v_ashrrev_i32_e32 v1, 6, v75
	v_lshlrev_b32_e32 v2, 4, v76
	v_mul_lo_u32 v1, v1, s29
	v_and_b32_e32 v2, 0x1f0, v2
	v_add3_u32 v1, v0, v1, v2
	ds_write_b128 v1, v[54:57]
	v_ashrrev_i32_e32 v1, 6, v77
	v_lshlrev_b32_e32 v2, 4, v78
	v_mul_lo_u32 v1, v1, s29
	v_and_b32_e32 v2, 0x1f0, v2
	v_add3_u32 v1, v0, v1, v2
	ds_write_b128 v1, v[58:61]
	v_ashrrev_i32_e32 v1, 6, v79
	v_lshlrev_b32_e32 v2, 4, v80
	v_mul_lo_u32 v1, v1, s29
	v_and_b32_e32 v2, 0x1f0, v2
	v_add3_u32 v0, v0, v1, v2
	ds_write_b128 v0, v[62:65]
	s_and_saveexec_b64 s[0:1], vcc
	s_cbranch_execz .LBB0_1146
	s_mul_i32 s7, s45, 0x4200
	s_add_u32 s10, s19, s7
	s_addc_u32 s11, s20, 0
	v_add_u32_e32 v4, 0xfffffe00, v172
	v_lshl_add_u32 v5, v172, 4, s31
	v_lshlrev_b32_e32 v2, 3, v172
	s_mov_b64 s[12:13], 0
